# de-phase sub-group step 2.5us (was 3us); otherwise as previous (nt epilogue stores, qg16 MFMA skip, max fold, P4 epilogue batching)
# speedup vs baseline: 1.0350x; 1.0067x over previous
.LBB0_402:
	v_writelane_b32 v252, s14, 54
	v_writelane_b32 v252, s86, 56
	s_nop 1
	v_writelane_b32 v252, s87, 57
	v_writelane_b32 v252, s84, 58
	s_nop 1
	v_writelane_b32 v252, s85, 59
	v_writelane_b32 v252, s68, 60
	s_nop 1
	v_writelane_b32 v253, s72, 0
	v_writelane_b32 v252, s69, 61
	v_writelane_b32 v253, s73, 1
	v_writelane_b32 v252, s70, 62
	v_writelane_b32 v253, s74, 2
	v_writelane_b32 v252, s71, 63
	v_writelane_b32 v253, s75, 3
	s_or_b64 exec, exec, s[0:1]
	s_add_u32 s18, s76, 0xa000000
	s_addc_u32 s19, s77, 0
	s_cmpk_lt_i32 s26, 0xe80
	s_cselect_b64 s[0:1], -1, 0
	s_add_u32 s15, s76, 0x7800000
	s_addc_u32 s88, s77, 0
	v_writelane_b32 v253, s0, 4
	s_add_u32 s89, s76, 0x8000000
	s_addc_u32 s90, s77, 0
	v_writelane_b32 v253, s1, 5
	s_bfe_u32 s0, s82, 0x20006
	s_lshr_b32 s1, s82, 8
	s_cmp_eq_u32 s1, 1
	s_cselect_b64 s[10:11], -1, 0
	s_lshl_b32 s2, s1, 6
	s_lshl_b32 s17, s1, 13
	s_or_b32 s1, s2, 16
	v_writelane_b32 v253, s1, 6
	s_lshl_b32 s65, s1, 7
	s_or_b32 s1, s2, 32
	v_writelane_b32 v253, s1, 7
	s_lshl_b32 s1, s1, 7
	v_writelane_b32 v253, s1, 8
	v_writelane_b32 v253, s2, 10
	s_or_b32 s1, s2, 48
	v_writelane_b32 v253, s1, 11
	s_lshl_b32 s1, s1, 7
	s_lshl_b32 s64, s0, 12
	v_writelane_b32 v253, s1, 12
	s_mov_b32 s2, s82
	v_writelane_b32 v253, s2, 14
	s_cmpk_lt_u32 s82, 0x100
	v_cndmask_b32_e64 v192, 0, 1, s[10:11]
	v_writelane_b32 v253, s3, 15
	s_cselect_b64 s[2:3], -1, 0
	v_writelane_b32 v253, s2, 16
	s_lshl_b32 s0, s0, 5
	s_barrier
	v_writelane_b32 v253, s3, 17
	v_writelane_b32 v253, s0, 18
	s_add_u32 s0, s76, 0x12000000
	s_addc_u32 s1, s77, 0
	v_writelane_b32 v253, s0, 19
	s_cmpk_gt_i32 s26, 0xe7f
	s_nop 0
	v_writelane_b32 v253, s1, 20
	s_mov_b32 s0, s26
	v_writelane_b32 v253, s0, 21
	s_mov_b32 s26, s80
	s_nop 0
	v_writelane_b32 v253, s1, 22
	v_writelane_b32 v253, s27, 23
	s_cbranch_scc1 .LBB0_549
	s_add_u32 s91, s76, 0x5800000
	v_readlane_b32 s0, v253, 8
	s_addc_u32 s92, s77, 0
	s_add_i32 s96, s0, 0
	v_readlane_b32 s0, v253, 12
	s_add_i32 s25, s64, 0
	s_add_i32 s97, s0, 0
	v_readlane_b32 s0, v253, 21
	s_mov_b32 s23, 0
	s_add_i32 s93, s25, 0x10000
	s_add_i32 s94, s17, 0
	s_add_i32 s95, s65, 0
	s_add_i32 s12, s25, 0x14000
	s_add_i32 s13, s25, 0x18000
	s_add_i32 s25, s25, 0x1c000
	s_add_i32 s33, s0, 0xfffff200
	s_lshl_b32 s84, s0, 8
	s_lshl_b32 s85, s80, 8
	s_mov_b64 s[44:45], 0x80
	s_mov_b64 s[46:47], 0x5800080
	s_mov_b64 s[48:49], 0x4900100
	s_mov_b64 s[50:51], 0x5800100
	s_mov_b64 s[52:53], 0x4980100
	s_mov_b64 s[54:55], 0x4900180
	s_mov_b64 s[56:57], 0x5800180
	s_mov_b64 s[58:59], 0x4980180
	s_mov_b64 s[60:61], 0x100
	s_mov_b64 s[62:63], 0xf80
	v_mov_b32_e32 v129, 0
	s_mov_b64 s[66:67], 0xa000080
	s_mov_b64 s[68:69], 0xa000100
	s_mov_b64 s[70:71], 0x80100
	s_mov_b64 s[72:73], 0x180
	s_mov_b64 s[74:75], 0xa000180
	s_mov_b64 s[8:9], 0x80180
	s_movk_i32 s86, 0x3800
	v_mov_b32_e32 v146, 1
	v_mov_b32_e32 v147, 0x1000
	v_mov_b32_e32 v148, 0x2000
	v_mov_b32_e32 v149, 0x3000
	v_readlane_b32 s87, v252, 54
	s_mov_b32 s40, s0
	v_readlane_b32 s1, v253, 22
	s_cmpk_lt_u32 s40, 0x80
	s_cbranch_scc1 .Lp1_lo
	s_mov_b32 s98, 62
	s_bfe_u32 s99, s40, 0x20003
	s_mul_i32 s99, s99, 5
	s_add_u32 s98, s98, s99
	s_branch .Lp1_go
.Lp1_lo:
	s_mov_b32 s98, 0
	s_bfe_u32 s99, s40, 0x20003
	s_mul_i32 s99, s99, 5
	s_add_u32 s98, s98, s99

.LBB0_627:
	s_add_u32 s0, s76, 0x2e000000
	s_addc_u32 s1, s77, 0
	v_writelane_b32 v253, s0, 40
	s_add_u32 s2, s76, 0x22000000
	s_addc_u32 s3, s77, 0
	v_writelane_b32 v253, s1, 41
	s_nop 0
	v_readlane_b32 s0, v253, 4
	v_readlane_b32 s1, v253, 5
	s_andn2_b64 vcc, exec, s[0:1]
	s_barrier
	s_cbranch_vccnz .LBB0_691
	v_readlane_b32 s0, v253, 28
	s_add_i32 s57, s0, 0
	v_readlane_b32 s0, v253, 30
	s_add_i32 s58, s0, 0
	v_readlane_b32 s0, v253, 8
	s_add_i32 s63, s64, 0
	s_add_i32 s59, s0, 0
	v_readlane_b32 s0, v253, 12
	s_mov_b32 s9, 0
	s_add_i32 s56, s63, 0x10000
	s_add_i32 s60, s0, 0
	s_add_i32 s61, s63, 0x14000
	s_add_i32 s62, s63, 0x18000
	s_add_i32 s63, s63, 0x1c000
	s_add_i32 s66, s78, 0xfffffa00
	s_lshl_b32 s67, s78, 8
	s_lshl_b32 s68, s80, 8
	s_add_i32 s69, 0, 0x10000
	s_add_i32 s70, 0, 0x14000
	s_mov_b64 s[12:13], 0x80
	s_mov_b64 s[14:15], 0x12000080
	s_mov_b64 s[16:17], 0x3000100
	s_mov_b64 s[18:19], 0x12000100
	s_mov_b64 s[20:21], 0x3080100
	s_mov_b64 s[22:23], 0x3000180
	s_mov_b64 s[36:37], 0x12000180
	s_mov_b64 s[38:39], 0x3080180
	s_mov_b64 s[40:41], 0x100
	s_mov_b64 s[42:43], 0xf80
	s_movk_i32 s71, 0x1080
	s_movk_i32 s72, 0x2100
	s_mov_b64 s[44:45], 0x2400100
	s_mov_b64 s[46:47], 0x2480100
	s_mov_b64 s[48:49], 0x2400180
	s_mov_b64 s[50:51], 0x2480180
	s_movk_i32 s73, 0x1800
	v_mov_b32_e32 v129, 0
	v_mov_b32_e32 v146, 1
	s_mov_b32 s74, s78
	s_mov_b32 s75, s78
	s_cmpk_lt_u32 s75, 0x80
	s_cbranch_scc1 .Lp6_lo
	s_mov_b32 s98, 62
	s_bfe_u32 s99, s75, 0x20003
	s_mul_i32 s99, s99, 5
	s_add_u32 s98, s98, s99
	s_branch .Lp6_go
.Lp6_lo:
	s_mov_b32 s98, 0
	s_bfe_u32 s99, s75, 0x20003
	s_mul_i32 s99, s99, 5
	s_add_u32 s98, s98, s99
